# v069 stack + GEMM phase prologues issue K-step 0 and K-step 1 LDS-DMA pieces together (first wait vmcnt 2->8 moved behind them)
# baseline (speedup 1.0000x reference)
.LBB0_457:
	s_add_i32 m0, s44, 0x18000
	v_lshl_add_u64 v[8:9], v[8:9], 0, s[80:81]
	s_and_b32 s3, s4, 3
	s_lshl_b32 s88, s2, 6
	global_load_lds_dwordx4 v[8:9], off
	v_lshl_add_u64 v[6:7], v[6:7], 0, s[80:81]
	s_add_i32 m0, s44, 0x1a000
	s_add_i32 s1, s44, 0x8000
	s_add_i32 s0, s44, 0xa000
	global_load_lds_dwordx4 v[6:7], off
	v_lshl_add_u64 v[2:3], v[2:3], 0, s[80:81]
	s_mov_b32 m0, s1
	s_add_u32 s14, s10, 0x40080
	global_load_lds_dwordx4 v[2:3], off
	v_lshl_add_u64 v[2:3], v[4:5], 0, s[80:81]
	s_mov_b32 m0, s0
	s_addc_u32 s15, s11, 0
	global_load_lds_dwordx4 v[2:3], off
	s_add_i32 m0, s44, 0x1c000
	v_lshl_add_u64 v[2:3], s[14:15], 0, v[0:1]
	global_load_lds_dwordx4 v[2:3], off
	v_lshl_add_u64 v[2:3], s[14:15], 0, v[182:183]
	s_add_i32 m0, s44, 0x1e000
	v_ashrrev_i32_e32 v4, 4, v10
	global_load_lds_dwordx4 v[2:3], off
	s_waitcnt vmcnt(8)
	s_barrier
	v_and_b32_e32 v208, 15, v10
	v_lshlrev_b32_e32 v2, 3, v4
	v_and_b32_e32 v3, 48, v10
	v_and_b32_e32 v5, 0xfffffc00, v14
	v_lshlrev_b32_e32 v7, 2, v10
	v_lshl_add_u32 v6, s2, 13, v5
	v_lshl_or_b32 v3, v208, 6, v3
	v_and_b32_e32 v7, 32, v7
	v_lshl_add_u32 v5, s3, 12, v5
	v_lshl_add_u32 v210, s3, 5, v2
	v_lshlrev_b32_e32 v2, 2, v4
	v_bitop3_b32 v6, v3, v6, v7 bitop3:0xde
	v_bitop3_b32 v209, v3, v5, v7 bitop3:0xde
	v_ashrrev_i32_e32 v3, 31, v2
	v_lshl_add_u64 v[184:185], v[2:3], 2, s[24:25]
	v_lshlrev_b32_e32 v2, 14, v11
	v_and_b32_e32 v2, 0xffff8000, v2
	v_lshl_add_u32 v2, v12, 11, v2
	v_and_b32_e32 v3, 1, v11
	v_lshl_or_b32 v2, v3, 6, v2
	v_lshl_add_u32 v186, v13, 1, v2
	v_lshlrev_b32_e32 v2, 14, v15
	v_and_b32_e32 v2, 0xffff8000, v2
	s_waitcnt vmcnt(6)
	s_cmp_lt_u32 s4, 4
	v_lshl_add_u32 v2, v16, 11, v2
	v_and_b32_e32 v3, 1, v15
	s_cselect_b64 s[96:97], -1, 0
	s_bitcmp0_b32 s4, 0
	v_lshl_or_b32 v2, v3, 6, v2
	v_and_b32_e32 v211, 16, v10
	s_mov_b32 s68, 0
	s_cselect_b64 s[2:3], -1, 0
	v_cmp_gt_i32_e64 s[4:5], 2, v4
	v_or_b32_e32 v212, 16, v208
	v_or_b32_e32 v213, 32, v208
	v_or_b32_e32 v214, 48, v208
	v_mov_b32_e32 v187, v1
	v_lshl_add_u32 v188, v17, 1, v2
	v_mov_b32_e32 v189, v1
	v_add_u32_e32 v215, 0, v6
	s_barrier
	s_branch .LBB0_460

.LBB0_1088:
	v_and_b32_e32 v18, 15, v10
	v_and_b32_e32 v17, 0xfffffc00, v17
	v_lshl_or_b32 v249, s2, 6, v18
	v_lshl_add_u32 v21, s2, 13, v17
	v_readlane_b32 s2, v255, 16
	v_readlane_b32 s3, v255, 17
	s_mul_i32 s36, s2, 0x19800
	s_and_b32 s64, s16, 3
	s_lshl_b64 s[2:3], s[36:37], 2
	s_add_u32 s2, s46, s2
	s_addc_u32 s3, s47, s3
	s_add_u32 s65, s2, 0x102000
	s_addc_u32 s66, s3, 0
	s_add_u32 s10, s46, 0x5400000
	s_addc_u32 s11, s47, 0
	v_readlane_b32 s12, v255, 24
	v_readlane_b32 s13, v255, 25
	s_waitcnt lgkmcnt(0)
	s_add_u32 s12, s48, s12
	s_addc_u32 s13, s49, s13
	s_add_u32 s67, s2, 0x104000
	s_addc_u32 s68, s3, 0
	s_lshl_b64 s[2:3], s[6:7], 2
	s_add_u32 s2, s46, s2
	s_addc_u32 s3, s47, s3
	s_add_u32 s14, s2, 0x800000
	s_addc_u32 s15, s3, 0
	s_add_i32 m0, s56, 0x18000
	v_lshl_add_u64 v[8:9], v[8:9], 0, s[80:81]
	global_load_lds_dwordx4 v[8:9], off
	v_lshl_add_u64 v[6:7], v[6:7], 0, s[80:81]
	s_add_i32 m0, s56, 0x1a000
	s_add_i32 s70, s56, 0x8000
	s_add_i32 s71, s56, 0xa000
	global_load_lds_dwordx4 v[6:7], off
	v_lshl_add_u64 v[2:3], v[2:3], 0, s[80:81]
	s_mov_b32 m0, s70
	s_add_u32 s2, s50, 0x40080
	global_load_lds_dwordx4 v[2:3], off
	v_lshl_add_u64 v[2:3], v[4:5], 0, s[80:81]
	s_mov_b32 m0, s71
	s_addc_u32 s3, s51, 0
	global_load_lds_dwordx4 v[2:3], off
	s_add_i32 m0, s56, 0x1c000
	v_lshl_add_u64 v[2:3], s[2:3], 0, v[0:1]
	global_load_lds_dwordx4 v[2:3], off
	v_lshl_add_u64 v[2:3], s[2:3], 0, v[214:215]
	s_add_i32 m0, s56, 0x1e000
	v_and_b32_e32 v20, 48, v10
	global_load_lds_dwordx4 v[2:3], off
	s_waitcnt vmcnt(8)
	s_barrier
	v_lshlrev_b32_e32 v2, 14, v11
	v_and_b32_e32 v2, 0xffff8000, v2
	v_lshl_add_u32 v2, v12, 11, v2
	v_and_b32_e32 v3, 1, v11
	v_lshl_or_b32 v2, v3, 6, v2
	v_lshl_add_u32 v216, v13, 1, v2
	v_lshlrev_b32_e32 v2, 14, v14
	v_lshl_or_b32 v18, v18, 6, v20
	v_lshlrev_b32_e32 v20, 2, v10
	s_cmp_lt_u32 s16, 4
	v_readlane_b32 s18, v255, 13
	v_and_b32_e32 v2, 0xffff8000, v2
	v_ashrrev_i32_e32 v19, 1, v10
	v_and_b32_e32 v20, 32, v20
	s_waitcnt vmcnt(6)
	s_cselect_b64 s[16:17], -1, 0
	s_lshr_b32 s76, s18, 1
	v_lshl_add_u32 v2, v15, 11, v2
	v_and_b32_e32 v3, 1, v14
	v_and_b32_e32 v19, -8, v19
	v_bitop3_b32 v21, v18, v21, v20 bitop3:0xde
	v_lshl_add_u32 v17, s64, 12, v17
	s_and_b64 s[18:19], s[82:83], exec
	v_lshl_or_b32 v2, v3, 6, v2
	v_bitop3_b32 v245, v18, v17, v20 bitop3:0xde
	v_lshl_add_u32 v246, s64, 5, v19
	v_cmp_gt_u32_e64 s[2:3], 16, v10
	s_cselect_b32 s77, 2, 1
	s_mov_b32 s78, 0
	v_mov_b32_e32 v217, v1
	v_lshl_add_u32 v218, v16, 1, v2
	v_mov_b32_e32 v219, v1
	v_add_u32_e32 v252, 0, v21
	s_barrier
	s_branch .LBB0_1091

.LBB0_1242:
	v_readlane_b32 s4, v255, 16
	v_readlane_b32 s5, v255, 17
	s_mul_i32 s14, s4, 0x5d800
	s_add_u32 s4, s8, 0x9c00000
	s_addc_u32 s5, s9, 0
	s_lshl_b64 s[6:7], s[6:7], 2
	s_add_u32 s10, s8, s6
	s_addc_u32 s11, s9, s7
	s_add_u32 s6, s8, s14
	s_addc_u32 s7, s9, 0
	s_add_u32 s38, s6, 0x300000
	s_addc_u32 s39, s7, 0
	s_lshl_b32 s6, s12, 5
	s_and_b32 s40, s6, 0x60
	s_add_i32 m0, s31, 0x18000
	v_lshl_add_u64 v[8:9], v[8:9], 0, s[80:81]
	v_ashrrev_i32_e32 v19, 6, v16
	s_lshr_b32 s6, s40, 3
	global_load_lds_dwordx4 v[8:9], off
	v_lshl_add_u64 v[6:7], v[6:7], 0, s[80:81]
	s_add_i32 m0, s31, 0x1a000
	s_add_i32 s41, s31, 0x8000
	s_add_i32 s42, s31, 0xa000
	v_lshlrev_b32_e32 v21, 10, v19
	v_add_lshl_u32 v19, s6, v19, 10
	global_load_lds_dwordx4 v[6:7], off
	v_lshl_add_u64 v[2:3], v[2:3], 0, s[80:81]
	s_mov_b32 m0, s41
	s_add_u32 s6, s22, 0x40080
	global_load_lds_dwordx4 v[2:3], off
	v_lshl_add_u64 v[2:3], v[4:5], 0, s[80:81]
	s_mov_b32 m0, s42
	s_addc_u32 s7, s23, 0
	global_load_lds_dwordx4 v[2:3], off
	s_add_i32 m0, s31, 0x1c000
	v_lshl_add_u64 v[2:3], s[6:7], 0, v[0:1]
	global_load_lds_dwordx4 v[2:3], off
	v_lshl_add_u64 v[2:3], s[6:7], 0, v[146:147]
	s_add_i32 m0, s31, 0x1e000
	v_ashrrev_i32_e32 v18, 4, v16
	global_load_lds_dwordx4 v[2:3], off
	s_waitcnt vmcnt(8)
	s_barrier
	v_lshlrev_b32_e32 v2, 2, v18
	v_ashrrev_i32_e32 v3, 31, v2
	v_lshl_add_u64 v[2:3], v[2:3], 2, s[10:11]
	s_mov_b64 s[8:9], 0x800000
	v_lshl_add_u64 v[154:155], v[2:3], 0, s[8:9]
	v_lshlrev_b32_e32 v2, 14, v13
	v_and_b32_e32 v2, 0xffff8000, v2
	v_lshl_add_u32 v2, v14, 11, v2
	v_and_b32_e32 v3, 1, v13
	v_lshl_or_b32 v2, v3, 6, v2
	v_lshl_add_u32 v156, v15, 1, v2
	v_lshlrev_b32_e32 v2, 14, v10
	v_and_b32_e32 v17, 15, v16
	v_and_b32_e32 v20, 48, v16
	v_lshlrev_b32_e32 v16, 2, v16
	v_and_b32_e32 v2, 0xffff8000, v2
	v_lshl_or_b32 v167, s13, 6, v17
	v_lshl_add_u32 v21, s13, 13, v21
	v_lshl_or_b32 v17, v17, 6, v20
	v_and_b32_e32 v16, 32, v16
	s_waitcnt vmcnt(6)
	v_lshl_add_u32 v2, v11, 11, v2
	v_and_b32_e32 v3, 1, v10
	v_lshlrev_b32_e32 v152, 3, v18
	v_bitop3_b32 v20, v17, v21, v16 bitop3:0xde
	s_cmp_lt_u32 s12, 4
	v_lshl_or_b32 v2, v3, 6, v2
	v_bitop3_b32 v171, v19, v17, v16 bitop3:0xf6
	s_cselect_b64 s[6:7], -1, 0
	v_ashrrev_i32_e32 v153, 31, v152
	v_mov_b32_e32 v157, v1
	v_lshl_add_u32 v158, v12, 1, v2
	v_mov_b32_e32 v159, v1
	s_mov_b32 s43, 0
	v_add_u32_e32 v175, 0, v20
	s_barrier
	s_branch .LBB0_1245

.LBB0_1319:
	s_add_u32 s66, s18, 0x22ec00
	s_addc_u32 s67, s19, 0
	s_add_u32 s26, s18, 0x400000
	s_addc_u32 s27, s19, 0
	v_and_b32_e32 v17, 0xfffffc00, v17
	s_add_i32 m0, s62, 0x18000
	v_lshl_add_u64 v[8:9], v[8:9], 0, s[80:81]
	s_and_b32 s3, s2, 3
	s_lshl_b32 s0, s1, 6
	v_lshl_add_u32 v21, s1, 13, v17
	global_load_lds_dwordx4 v[8:9], off
	v_lshl_add_u64 v[6:7], v[6:7], 0, s[80:81]
	s_add_i32 m0, s62, 0x1a000
	s_add_i32 s1, s62, 0x8000
	s_add_i32 s68, s62, 0xa000
	global_load_lds_dwordx4 v[6:7], off
	v_lshl_add_u64 v[2:3], v[2:3], 0, s[80:81]
	s_mov_b32 m0, s1
	s_add_u32 s4, s8, 0x40080
	global_load_lds_dwordx4 v[2:3], off
	v_lshl_add_u64 v[2:3], v[4:5], 0, s[80:81]
	s_mov_b32 m0, s68
	s_addc_u32 s5, s9, 0
	global_load_lds_dwordx4 v[2:3], off
	s_add_i32 m0, s62, 0x1c000
	v_lshl_add_u64 v[2:3], s[4:5], 0, v[0:1]
	global_load_lds_dwordx4 v[2:3], off
	v_lshl_add_u64 v[2:3], s[4:5], 0, v[178:179]
	s_add_i32 m0, s62, 0x1e000
	v_ashrrev_i32_e32 v18, 4, v10
	global_load_lds_dwordx4 v[2:3], off
	s_waitcnt vmcnt(8)
	s_barrier
	v_lshlrev_b32_e32 v2, 2, v18
	v_ashrrev_i32_e32 v3, 31, v2
	v_lshl_add_u64 v[2:3], v[2:3], 2, s[18:19]
	s_mov_b64 s[10:11], 0xc80000
	v_lshl_add_u64 v[184:185], v[2:3], 0, s[10:11]
	v_lshlrev_b32_e32 v2, 14, v14
	v_and_b32_e32 v2, 0xffff8000, v2
	v_lshl_add_u32 v2, v15, 11, v2
	v_and_b32_e32 v3, 1, v14
	v_lshl_or_b32 v2, v3, 6, v2
	v_lshl_add_u32 v186, v16, 1, v2
	v_lshlrev_b32_e32 v2, 14, v11
	v_and_b32_e32 v206, 15, v10
	v_and_b32_e32 v20, 48, v10
	v_lshlrev_b32_e32 v22, 2, v10
	v_and_b32_e32 v2, 0xffff8000, v2
	v_lshl_or_b32 v20, v206, 6, v20
	v_and_b32_e32 v22, 32, v22
	s_waitcnt vmcnt(6)
	s_cmp_lt_u32 s2, 4
	v_lshl_add_u32 v2, v12, 11, v2
	v_and_b32_e32 v3, 1, v11
	v_lshlrev_b32_e32 v19, 3, v18
	v_bitop3_b32 v21, v20, v21, v22 bitop3:0xde
	v_lshl_add_u32 v17, s3, 12, v17
	s_cselect_b64 s[28:29], -1, 0
	s_bitcmp0_b32 s2, 0
	v_lshl_or_b32 v2, v3, 6, v2
	v_bitop3_b32 v207, v20, v17, v22 bitop3:0xde
	v_lshl_add_u32 v208, s3, 5, v19
	v_and_b32_e32 v209, 16, v10
	s_mov_b32 s70, 0
	s_cselect_b64 s[2:3], -1, 0
	v_cmp_gt_i32_e64 s[4:5], 2, v18
	v_or_b32_e32 v210, 16, v206
	v_or_b32_e32 v211, 32, v206
	v_or_b32_e32 v212, 48, v206
	v_mov_b32_e32 v187, v1
	v_lshl_add_u32 v188, v13, 1, v2
	v_mov_b32_e32 v189, v1
	v_add_u32_e32 v213, 0, v21
	v_readlane_b32 s33, v254, 26
	v_readlane_b32 s34, v254, 25
	s_barrier
	s_branch .LBB0_1322

.LBB0_1429:
	s_add_u32 s12, s18, 0x1aa00000
	s_addc_u32 s13, s19, 0
	s_and_b64 s[14:15], s[20:21], exec
	s_cselect_b32 s47, s85, 64
	s_add_u32 s20, s18, 0x16200000
	s_addc_u32 s21, s19, 0
	s_and_b64 s[14:15], s[82:83], exec
	s_waitcnt lgkmcnt(0)
	s_cselect_b32 s15, s9, s21
	s_cselect_b32 s14, s8, s20
	s_add_u32 s20, s24, s51
	s_addc_u32 s21, s25, s52
	s_add_u32 s54, s20, 0x105000
	s_addc_u32 s55, s21, 0
	s_add_u32 s20, s18, 0x5400000
	s_addc_u32 s21, s19, 0
	s_add_u32 s22, s2, 0x1000
	s_addc_u32 s23, s3, 0
	s_add_u32 s56, s18, 0x167000
	s_addc_u32 s57, s19, 0
	v_readlane_b32 s2, v255, 6
	v_readlane_b32 s3, v255, 7
	s_add_u32 s2, s18, s2
	s_addc_u32 s3, s19, s3
	s_add_u32 s18, s2, 0xc80000
	s_addc_u32 s19, s3, 0
	s_add_i32 m0, s33, 0x18000
	v_lshl_add_u64 v[8:9], v[8:9], 0, s[80:81]
	s_and_b32 s58, s4, 3
	global_load_lds_dwordx4 v[8:9], off
	v_lshl_add_u64 v[6:7], v[6:7], 0, s[80:81]
	s_add_i32 m0, s33, 0x1a000
	s_add_i32 s59, s33, 0x8000
	s_add_i32 s61, s33, 0xa000
	global_load_lds_dwordx4 v[6:7], off
	v_lshl_add_u64 v[2:3], v[2:3], 0, s[80:81]
	s_mov_b32 m0, s59
	s_add_u32 s2, s30, 0xb0080
	global_load_lds_dwordx4 v[2:3], off
	v_lshl_add_u64 v[2:3], v[4:5], 0, s[80:81]
	s_mov_b32 m0, s61
	s_addc_u32 s3, s31, 0
	global_load_lds_dwordx4 v[2:3], off
	s_add_i32 m0, s33, 0x1c000
	v_lshl_add_u64 v[2:3], s[2:3], 0, v[0:1]
	global_load_lds_dwordx4 v[2:3], off
	v_lshl_add_u64 v[2:3], s[2:3], 0, v[170:171]
	s_add_i32 m0, s33, 0x1e000
	s_movk_i32 s26, 0xb00
	global_load_lds_dwordx4 v[2:3], off
	s_waitcnt vmcnt(8)
	s_barrier
	v_and_b32_e32 v20, 15, v10
	v_and_b32_e32 v19, 0xfffffc00, v19
	v_lshrrev_b32_e32 v3, 1, v11
	v_mul_lo_u32 v2, v13, s26
	s_mov_b32 s27, 0xb000
	v_lshl_or_b32 v202, s5, 6, v20
	v_lshl_add_u32 v23, s5, 13, v19
	s_cmp_lt_u32 s4, 4
	v_mad_u64_u32 v[2:3], s[4:5], v3, s27, v[2:3]
	v_or_b32_e32 v2, v2, v12
	v_add_lshl_u32 v2, v2, v14, 1
	v_mov_b32_e32 v3, v1
	s_mov_b64 s[28:29], 0xb0080
	v_and_b32_e32 v22, 48, v10
	v_lshl_add_u64 v[172:173], v[2:3], 0, s[28:29]
	v_lshrrev_b32_e32 v3, 1, v15
	v_mul_lo_u32 v2, v17, s26
	v_lshl_or_b32 v20, v20, 6, v22
	v_lshlrev_b32_e32 v22, 2, v10
	v_mad_u64_u32 v[2:3], s[4:5], v3, s27, v[2:3]
	v_ashrrev_i32_e32 v21, 1, v10
	v_and_b32_e32 v22, 32, v22
	s_waitcnt vmcnt(6)
	v_or_b32_e32 v2, v2, v16
	v_and_b32_e32 v21, -8, v21
	v_bitop3_b32 v23, v20, v23, v22 bitop3:0xde
	v_lshl_add_u32 v19, s58, 12, v19
	v_add_lshl_u32 v2, v2, v18, 1
	v_mov_b32_e32 v3, v1
	v_bitop3_b32 v203, v20, v19, v22 bitop3:0xde
	s_cselect_b64 s[24:25], -1, 0
	v_lshl_add_u32 v204, s58, 5, v21
	v_cmp_gt_u32_e64 s[2:3], 16, v10
	s_lshr_b32 s62, s1, 3
	v_lshl_add_u64 v[174:175], v[2:3], 0, s[28:29]
	s_mov_b32 s60, 0
	v_add_u32_e32 v205, 0, v23
	s_barrier
	s_branch .LBB0_1432
